# P0: modulation tasks moved off the 32 workgroups that convert two weight items per wave (t = wave*224 + vcu-32 for vcu>=32)
# baseline (speedup 1.0000x reference)
.Lxb_place_ok:
.LBB0_11:
	s_or_b64 exec, exec, s[2:3]
	s_load_dwordx2 s[4:5], s[0:1], 0xd8
	s_lshr_b32 s76, s73, 6
	v_and_b32_e32 v227, 63, v0
	s_mov_b32 s55, 1
	s_waitcnt lgkmcnt(0)
	s_cmp_lt_i32 s4, 1
	s_cselect_b64 s[2:3], -1, 0
	v_writelane_b32 v250, s4, 8
	s_cmp_gt_i32 s5, 0
	s_nop 0
	v_writelane_b32 v250, s5, 9
	s_cselect_b64 s[4:5], -1, 0
	s_and_b64 s[2:3], s[2:3], s[4:5]
	v_writelane_b32 v250, s2, 10
	s_andn2_b64 vcc, exec, s[2:3]
	s_nop 0
	v_writelane_b32 v250, s3, 11
	s_cbranch_vccnz .LBB0_68
	s_cmp_lt_i32 s55, 1
	s_cbranch_scc1 .LBB0_68
	v_writelane_b32 v250, s73, 12
	s_cmpk_eq_i32 s33, 0x100
	s_movk_i32 s2, 0x900
	v_readlane_b32 s3, v250, 3
	s_cselect_b32 s54, s2, 0x3b00
	s_lshl_b32 s2, s3, 3
	s_add_i32 s2, s2, s76
	s_cmp_lt_i32 s2, s54
	v_writelane_b32 v250, s2, 13
	s_cselect_b64 s[40:41], -1, 0
	s_lshl_b32 s2, s76, 14
	s_add_i32 s2, s2, 0
	s_lshl_b32 s56, s33, 3
	s_load_dwordx4 s[28:31], s[0:1], 0x28
	s_load_dwordx4 s[36:39], s[0:1], 0x48
	s_add_u32 s57, s86, 0xc00000
	s_addc_u32 s52, s87, 0
	s_add_u32 s53, s86, 0x100000
	s_addc_u32 s60, s87, 0
	s_waitcnt lgkmcnt(0)
	s_add_u32 s42, s28, 0x1000
	s_addc_u32 s43, s29, 0
	s_add_u32 s44, s30, 0x1000
	s_addc_u32 s45, s31, 0
	s_add_u32 s50, s30, 0x2000
	s_addc_u32 s51, s31, 0
	s_add_u32 s58, s30, 0x3000
	s_addc_u32 s59, s31, 0
	s_add_u32 s4, s30, 0x4000
	v_writelane_b32 v250, s2, 14
	s_addc_u32 s5, s31, 0
	v_writelane_b32 v250, s4, 15
	s_mul_i32 s2, s33, s76
	v_mov_b32_e32 v31, 0
	v_writelane_b32 v250, s5, 16
	s_add_u32 s4, s30, 0x5000
	s_addc_u32 s5, s31, 0
	v_writelane_b32 v250, s4, 31
	s_mov_b32 s61, 0
	s_movk_i32 s62, 0x2000
	v_writelane_b32 v250, s5, 32
	s_add_u32 s4, s30, 0x6000
	s_addc_u32 s5, s31, 0
	v_writelane_b32 v250, s4, 33
	s_movk_i32 s63, 0x4000
	s_movk_i32 s64, 0x6000
	v_writelane_b32 v250, s5, 34
	s_add_u32 s4, s30, 0x7000
	s_addc_u32 s5, s31, 0
	v_writelane_b32 v250, s4, 35
	s_mov_b32 s65, 0x8000
	s_mov_b32 s66, 0xa000
	v_writelane_b32 v250, s5, 36
	s_add_u32 s4, s30, 0x8000
	s_addc_u32 s5, s31, 0
	v_writelane_b32 v250, s4, 37
	s_mov_b32 s67, 0xc000
	s_mov_b32 s68, 0xe000
	v_writelane_b32 v250, s5, 38
	s_add_u32 s4, s30, 0x9000
	s_addc_u32 s5, s31, 0
	v_writelane_b32 v250, s4, 39
	s_mov_b32 s69, 0x10000
	s_mov_b32 s70, 0x12000
	v_writelane_b32 v250, s5, 40
	s_add_u32 s4, s30, 0xa000
	s_addc_u32 s5, s31, 0
	v_writelane_b32 v250, s4, 41
	s_mov_b32 s71, 0x14000
	s_mov_b32 s72, 0x16000
	v_writelane_b32 v250, s5, 42
	s_add_u32 s4, s30, 0xb000
	s_addc_u32 s5, s31, 0
	v_writelane_b32 v250, s4, 43
	s_mov_b32 s73, 0x18000
	s_mov_b32 s74, 0x1a000
	v_writelane_b32 v250, s5, 44
	s_add_u32 s4, s30, 0xc000
	s_addc_u32 s5, s31, 0
	v_writelane_b32 v250, s4, 45
	s_mov_b32 s75, 0x1c000
	s_mov_b32 s77, 0x20000
	v_writelane_b32 v250, s5, 46
	s_add_u32 s4, s30, 0xd000
	s_addc_u32 s5, s31, 0
	v_writelane_b32 v250, s4, 47
	s_mov_b32 s78, 0x22000
	s_mov_b32 s79, 0x24000
	v_writelane_b32 v250, s5, 48
	s_add_u32 s4, s30, 0xe000
	s_addc_u32 s5, s31, 0
	v_writelane_b32 v250, s4, 49
	s_mov_b32 s80, 0x26000
	s_mov_b32 s81, 0x28000
	v_writelane_b32 v250, s5, 50
	s_add_u32 s4, s30, 0xf000
	s_addc_u32 s5, s31, 0
	v_writelane_b32 v250, s4, 51
	s_mov_b32 s82, 0x2a000
	s_mov_b32 s83, 0x2c000
	v_writelane_b32 v250, s5, 52
	s_add_u32 s4, s30, 0x10000
	s_addc_u32 s5, s31, 0
	v_writelane_b32 v250, s4, 53
	s_mov_b32 s88, 0x2e000
	s_mov_b32 s89, 0x30000
	v_writelane_b32 v250, s5, 54
	s_add_u32 s4, s30, 0x11000
	s_addc_u32 s5, s31, 0
	v_writelane_b32 v250, s4, 55
	s_mov_b32 s90, 0x32000
	s_mov_b32 s91, 0x34000
	v_writelane_b32 v250, s5, 56
	s_add_u32 s4, s30, 0x12000
	s_addc_u32 s5, s31, 0
	v_writelane_b32 v250, s4, 57
	s_mov_b32 s92, 0x36000
	s_mov_b32 s93, 0x38000
	v_writelane_b32 v250, s5, 58
	s_add_u32 s4, s30, 0x13000
	s_addc_u32 s5, s31, 0
	v_writelane_b32 v250, s4, 59
	s_mov_b32 s94, 0x3a000
	s_mov_b32 s95, 0x3c000
	v_writelane_b32 v250, s5, 60
	s_add_u32 s4, s30, 0x14000
	s_addc_u32 s5, s31, 0
	v_writelane_b32 v250, s4, 61
	s_mov_b32 s96, 0x3e000
	s_movk_i32 s97, 0x7fff
	v_writelane_b32 v250, s5, 62
	s_add_u32 s4, s30, 0x15000
	s_addc_u32 s5, s31, 0
	v_writelane_b32 v250, s4, 63
	s_movk_i32 s34, 0x4800
	s_nop 0
	v_writelane_b32 v251, s5, 0
	s_add_u32 s4, s30, 0x16000
	s_addc_u32 s5, s31, 0
	v_writelane_b32 v251, s4, 1
	s_nop 1
	v_writelane_b32 v251, s5, 2
	s_add_u32 s4, s30, 0x17000
	s_addc_u32 s5, s31, 0
	v_writelane_b32 v251, s4, 3
	s_nop 1
	v_writelane_b32 v251, s5, 4
	s_add_u32 s4, s30, 0x18000
	s_addc_u32 s5, s31, 0
	v_writelane_b32 v251, s4, 5
	s_nop 1
	v_writelane_b32 v251, s5, 6
	s_add_u32 s4, s30, 0x19000
	s_addc_u32 s5, s31, 0
	v_writelane_b32 v251, s4, 7
	s_nop 1
	v_writelane_b32 v251, s5, 8
	s_add_u32 s4, s30, 0x1a000
	s_addc_u32 s5, s31, 0
	v_writelane_b32 v251, s4, 9
	s_nop 1
	v_writelane_b32 v251, s5, 10
	s_add_u32 s4, s30, 0x1b000
	s_addc_u32 s5, s31, 0
	v_writelane_b32 v251, s4, 11
	s_nop 1
	v_writelane_b32 v251, s5, 12
	s_add_u32 s4, s30, 0x1c000
	s_addc_u32 s5, s31, 0
	v_writelane_b32 v251, s4, 13
	s_nop 1
	v_writelane_b32 v251, s5, 14
	s_add_u32 s4, s30, 0x1d000
	s_addc_u32 s5, s31, 0
	v_writelane_b32 v251, s4, 15
	s_nop 1
	v_writelane_b32 v251, s5, 16
	s_add_u32 s4, s30, 0x1e000
	s_addc_u32 s5, s31, 0
	v_writelane_b32 v251, s4, 17
	s_nop 1
	v_writelane_b32 v251, s5, 18
	s_add_u32 s4, s30, 0x1f000
	s_addc_u32 s5, s31, 0
	v_writelane_b32 v251, s4, 19
	s_add_i32 s2, s3, s2
	s_cmpk_eq_i32 s33, 0x100
	s_cbranch_scc0 .Lp0map_done
	v_readlane_b32 s100, v250, 3
	s_mul_i32 s2, s76, 0xe0
	s_add_i32 s2, s2, s100
	s_sub_i32 s2, s2, 32
	s_cmp_lt_u32 s100, 32
	s_cselect_b32 s2, 0x300, s2
.Lp0map_done:
	s_cmpk_lt_i32 s2, 0x300
	v_writelane_b32 v251, s5, 20
	v_writelane_b32 v251, s76, 21
	v_writelane_b32 v251, s2, 22
	s_cselect_b64 s[2:3], -1, 0
	v_writelane_b32 v251, s2, 24
	s_cmp_lg_u64 s[38:39], 0
	s_cselect_b64 s[46:47], -1, 0
	v_writelane_b32 v251, s3, 25
	s_add_u32 s2, s36, 0x56a000
	s_addc_u32 s3, s37, 0
	s_load_dwordx2 s[36:37], s[0:1], 0x58
	s_load_dwordx8 s[20:27], s[0:1], 0x90
	v_writelane_b32 v251, s2, 26
	s_mov_b32 s76, 0x1e000
	s_nop 0
	v_writelane_b32 v251, s3, 27
	v_writelane_b32 v251, s58, 28
	s_mov_b32 s2, 0xffff0000
	s_movk_i32 s3, 0x5800
	v_writelane_b32 v251, s59, 29
	s_branch .LBB0_16
